# indexer unit prologue: both q_idx tile loads, the w_idx load and the first tile's k_idx fragments issued back-to-back with one wait (were three serialized vmcnt(0) waits)
# speedup vs baseline: 1.0118x; 1.0021x over previous
; #define LAS __attribute__((address_space(3)))
; __device__ __forceinline__ void sel_unit(LAS char* lds, int b, int u, const bf16_t* QI, const bf16_t* KIDX, const float* WIDX, unsigned long long* MASK) {
;     ...
; #pragma unroll
;     for (int i = 0; i < 2; ++i) { const int id = tid + 512 * i, row = id >> 6, ch = id & 63;
;         *(LAS u32x4*)(lds + L_QI + row * 1024 + ((ch ^ (row & 15)) << 4)) = *(const u32x4*)(QI + (rowbase + q0 + row) * 512 + ch * 8); }
;     for (int i = tid; i < 4096; i += 512) hist[i] = 0u;
;     if (tid < 16) { pref[tid] = 0u; kremS[tid] = 256u; }
;     if (tid < 128) ((LAS float*)(lds + L_W))[tid] = WIDX[(rowbase + q0 + (tid & 15)) * 8 + (tid >> 4)];
;     const LAS float* wl = (const LAS float*)(lds + L_W) + q16;
;     __syncthreads();
;     const int nj = (c - wid + 8) >> 3;
;     u32x4 sc[8][4];
; #pragma unroll
;     for (int j = 0; j < 8; ++j) {
;         if (j < nj) {
;             int t = wid + 8 * j; asm volatile("" : "+s"(t));
; #pragma unroll
;             for (int kh = 0; kh < 2; ++kh) {
;             bf16x8 kf[2][2];
; #pragma unroll
;             for (int kb = 0; kb < 2; ++kb)
; #pragma unroll
;                 for (int ks = 0; ks < 2; ++ks) kf[kb][ks] = *(const bf16x8*)(KIDX + (rowbase + 64 * t + 32 * kh + 16 * kb + q16) * 64 + 32 * ks + 8 * kg);
.LBB0_648:
	s_getreg_b32 s2, hwreg(HW_REG_HW_ID, 0, 6)
	s_lshl_b32 s2, s2, 2
	s_and_b32 s2, s2, 0xfc
	s_add_i32 s2, s2, 0x20040
	v_mov_b32_e32 v0, s2
	ds_read_b32 v0, v0
	s_ashr_i32 s1, s0, 31
	s_lshr_b32 s1, s1, 30
	s_add_i32 s2, s0, s1
	s_and_b32 s1, s2, -4
	s_sub_i32 s0, s0, s1
	s_waitcnt lgkmcnt(0)
	v_readfirstlane_b32 s1, v0
	v_mov_b32_e32 v0, v1
	s_lshl_b32 s2, s2, 2
	v_mbcnt_lo_u32_b32 v0, -1, v0
	v_mbcnt_hi_u32_b32 v2, -1, v0
	s_and_b32 s2, s2, -16
	v_lshl_or_b32 v58, s1, 6, v2
	s_ashr_i32 s1, s0, 31
	s_sub_i32 s2, 0xff0, s2
	s_lshl_b64 s[0:1], s[0:1], 12
	s_lshr_b32 s34, s2, 6
	s_add_u32 s52, s0, s2
	s_addc_u32 s53, s1, 0
	v_and_b32_e32 v59, 15, v2
	v_readfirstlane_b32 s47, v58
	s_cmpk_lt_u32 s2, 0x100
	s_mov_b64 s[2:3], -1
	s_cbranch_scc1 .LBB0_1103
	v_ashrrev_i32_e32 v10, 6, v58
	v_and_b32_e32 v3, 63, v2
	v_ashrrev_i32_e32 v11, 31, v10
	v_lshlrev_b32_e32 v0, 4, v3
	v_lshl_add_u64 v[4:5], s[52:53], 0, v[10:11]
	v_lshl_add_u64 v[8:9], s[70:71], 0, v[0:1]
	v_lshlrev_b64 v[4:5], 10, v[4:5]
	v_lshl_add_u64 v[4:5], v[8:9], 0, v[4:5]
	global_load_dwordx4 v[4:7], v[4:5], off
	v_lshlrev_b32_e32 v0, 10, v10
	v_bitop3_b32 v10, v10, v3, 15 bitop3:0x6c
	v_lshlrev_b32_e32 v10, 4, v10
	v_add3_u32 v44, 0, v0, v10
	v_add_u32_e32 v0, 0x200, v58
	v_ashrrev_i32_e32 v10, 6, v0
	v_ashrrev_i32_e32 v11, 31, v10
	v_lshl_add_u64 v[40:41], s[52:53], 0, v[10:11]
	v_lshlrev_b64 v[40:41], 10, v[40:41]
	v_lshl_add_u64 v[40:41], v[8:9], 0, v[40:41]
	global_load_dwordx4 v[40:43], v[40:41], off
	v_bitop3_b32 v3, v10, v3, 15 bitop3:0x6c
	v_lshlrev_b32_e32 v0, 10, v10
	v_lshlrev_b32_e32 v3, 4, v3
	v_add3_u32 v45, 0, v0, v3
	s_movk_i32 s2, 0x80
	v_cmp_gt_i32_e32 vcc, s2, v58
	s_and_saveexec_b64 s[2:3], vcc
	s_cbranch_execz .Lselpro_w
	v_mov_b32_e32 v47, s53
	v_or_b32_e32 v46, s52, v59
	v_ashrrev_i32_e32 v48, 4, v58
	v_lshlrev_b64 v[46:47], 5, v[46:47]
	v_ashrrev_i32_e32 v49, 31, v48
	v_lshl_add_u64 v[46:47], s[66:67], 0, v[46:47]
	v_lshl_add_u64 v[46:47], v[48:49], 2, v[46:47]
	global_load_dword v50, v[46:47], off
.Lselpro_w:
	s_or_b64 exec, exec, s[2:3]
	v_cmp_gt_i32_e32 vcc, s96, v58
	s_and_saveexec_b64 s[2:3], vcc
	s_cbranch_execz .LBB0_652
	v_lshlrev_b32_e32 v0, 5, v58
	v_mov_b64_e32 v[36:37], 0
	v_mov_b64_e32 v[38:39], 0
	ds_write_b128 v0, v[36:39] offset:16384
	ds_write_b128 v0, v[36:39] offset:16400
.LBB0_652:
	s_or_b64 exec, exec, s[2:3]
	v_cmp_gt_i32_e32 vcc, 16, v58
	v_lshl_add_u32 v0, v58, 2, 0
	s_and_saveexec_b64 s[2:3], vcc
	v_add_u32_e32 v3, 0x8800, v0
	v_mov_b32_e32 v51, 0x100
	ds_write2_b32 v3, v1, v51 offset0:16 offset1:32
	s_or_b64 exec, exec, s[2:3]
	s_waitcnt vmcnt(0)
	ds_write_b128 v44, v[4:7]
	ds_write_b128 v45, v[40:43]
	s_movk_i32 s2, 0x80
	v_cmp_gt_i32_e32 vcc, s2, v58
	s_and_saveexec_b64 s[2:3], vcc
	ds_write_b32 v0, v50 offset:35136
.LBB0_656:
	s_or_b64 exec, exec, s[2:3]
	s_ashr_i32 s46, s47, 6
	s_sub_i32 s2, s34, s46
	s_add_i32 s2, s2, 8
	s_ashr_i32 s4, s2, 3
	v_bfe_u32 v2, v2, 4, 2
	v_lshl_add_u32 v60, v59, 2, 0
	v_or_b32_e32 v18, s0, v59
	s_movk_i32 s0, 0x3fc
	s_cmp_gt_i32 s4, 0
	v_lshlrev_b32_e32 v0, 4, v2
	v_mad_u32_u24 v150, v59, s0, v60
	s_movk_i32 s0, 0xfc04
	s_cselect_b64 s[22:23], -1, 0
	v_mov_b32_e32 v19, s1
	v_lshl_add_u64 v[20:21], s[62:63], 0, v[0:1]
	v_mad_i32_i24 v0, v59, s0, v150
	s_and_b64 vcc, exec, s[22:23]
	v_xor_b32_e32 v182, v2, v59
	v_bitop3_b32 v183, v2, v59, 4 bitop3:0x36
	v_add_u32_e32 v137, 0x8800, v60
	v_bitop3_b32 v184, v2, v59, 8 bitop3:0x36
	v_bitop3_b32 v185, v2, v59, 12 bitop3:0x36
	v_bitop3_b32 v179, v2, v59, 16 bitop3:0x36
	v_bitop3_b32 v180, v2, v59, 20 bitop3:0x36
	v_bitop3_b32 v176, v2, v59, 24 bitop3:0x36
	v_bitop3_b32 v159, v2, v59, 28 bitop3:0x36
	v_bitop3_b32 v158, v2, v59, 32 bitop3:0x36
	v_bitop3_b32 v157, v2, v59, 36 bitop3:0x36
	v_bitop3_b32 v156, v2, v59, 40 bitop3:0x36
	v_bitop3_b32 v155, v2, v59, 44 bitop3:0x36
	v_bitop3_b32 v154, v2, v59, 48 bitop3:0x36
	v_bitop3_b32 v153, v2, v59, 52 bitop3:0x36
	v_bitop3_b32 v152, v2, v59, 56 bitop3:0x36
	v_bitop3_b32 v151, v2, v59, 60 bitop3:0x36
	v_lshl_add_u32 v182, v182, 4, v150
	v_lshl_add_u32 v183, v183, 4, v150
	v_lshl_add_u32 v184, v184, 4, v150
	v_lshl_add_u32 v185, v185, 4, v150
	v_lshl_add_u32 v179, v179, 4, v150
	v_lshl_add_u32 v180, v180, 4, v150
	v_lshl_add_u32 v176, v176, 4, v150
	v_lshl_add_u32 v159, v159, 4, v150
	v_lshl_add_u32 v158, v158, 4, v150
	v_lshl_add_u32 v157, v157, 4, v150
	v_lshl_add_u32 v156, v156, 4, v150
	v_lshl_add_u32 v155, v155, 4, v150
	v_lshl_add_u32 v154, v154, 4, v150
	v_lshl_add_u32 v153, v153, 4, v150
	v_lshl_add_u32 v152, v152, 4, v150
	v_lshl_add_u32 v151, v151, 4, v150
	s_mov_b32 s0, s46
	s_lshl_b32 s0, s0, 6
	s_ashr_i32 s1, s0, 31
	v_lshl_add_u64 v[2:3], v[18:19], 0, s[0:1]
	v_lshlrev_b64 v[2:3], 7, v[2:3]
	v_lshl_add_u64 v[22:23], v[20:21], 0, v[2:3]
	v_bfrev_b32_e32 v8, 1
	global_load_dwordx4 v[26:29], v[22:23], off
	global_load_dwordx4 v[30:33], v[22:23], off offset:64
	global_load_dwordx4 v[34:37], v[22:23], off offset:2048
	global_load_dwordx4 v[38:41], v[22:23], off offset:2112
	s_waitcnt lgkmcnt(0)
	s_barrier
	s_cbranch_vccz .LBB0_658
; #define LAS __attribute__((address_space(3)))
; __device__ __forceinline__ void sel_unit(LAS char* lds, int b, int u, const bf16_t* QI, const bf16_t* KIDX, const float* WIDX, unsigned long long* MASK) {
;     ...
;     for (int j = 0; j < 8; ++j) {
;         if (j < nj) {
;             int t = wid + 8 * j; asm volatile("" : "+s"(t));
; #pragma unroll
;             for (int kh = 0; kh < 2; ++kh) {
;             bf16x8 kf[2][2];
; #pragma unroll
;             for (int kb = 0; kb < 2; ++kb)
; #pragma unroll
;                 for (int ks = 0; ks < 2; ++ks) kf[kb][ks] = *(const bf16x8*)(KIDX + (rowbase + 64 * t + 32 * kh + 16 * kb + q16) * 64 + 32 * ks + 8 * kg);
; #pragma unroll
;             for (int kb = 0; kb < 2; ++kb) {
;                 f32x4 s = (f32x4){0.f, 0.f, 0.f, 0.f};
; #pragma unroll
;                 for (int hh = 0; hh < 8; ++hh) {
;                     f32x4 a = (f32x4){0.f, 0.f, 0.f, 0.f};
; #pragma unroll
;                     for (int ks = 0; ks < 2; ++ks) {
;                         const bf16x8 qv = *(const LAS bf16x8*)(lds + L_QI + q16 * 1024 + (((hh * 8 + 4 * ks + kg) ^ q16) << 4));
;                         a = __builtin_amdgcn_mfma_f32_16x16x32_bf16(kf[kb][ks], qv, a, 0, 0, 0);
;                     }
;                     const float wh = wl[hh * 16];
; #pragma unroll
;                     for (int i = 0; i < 4; ++i) s[i] += wh * fmaxf(a[i], 0.f);
;                 }
	ds_read_b128 v[230:233], v182
	ds_read_b128 v[234:237], v183
	ds_read_b32 v6, v137 offset:320
	s_waitcnt vmcnt(0)
	v_add_co_u32_e32 v22, vcc, s96, v22
	s_nop 1
	v_addc_co_u32_e32 v23, vcc, 0, v23, vcc
	global_load_dwordx4 v[42:45], v[22:23], off
	global_load_dwordx4 v[46:49], v[22:23], off offset:64
	global_load_dwordx4 v[50:53], v[22:23], off offset:2048
	global_load_dwordx4 v[2:5], v[22:23], off offset:2112
	s_waitcnt lgkmcnt(1)
	v_mfma_f32_16x16x32_bf16 v[246:249], v[26:29], v[230:233], 0
	v_mfma_f32_16x16x32_bf16 v[250:253], v[34:37], v[230:233], 0
	v_mfma_f32_16x16x32_bf16 v[246:249], v[30:33], v[234:237], v[246:249]
	v_mfma_f32_16x16x32_bf16 v[250:253], v[38:41], v[234:237], v[250:253]
	ds_read_b128 v[238:241], v184
	ds_read_b128 v[242:245], v185
	ds_read_b32 v7, v137 offset:384
	s_waitcnt lgkmcnt(1)
	v_mfma_f32_16x16x32_bf16 v[206:209], v[26:29], v[238:241], 0
	v_mfma_f32_16x16x32_bf16 v[210:213], v[34:37], v[238:241], 0
	v_mfma_f32_16x16x32_bf16 v[206:209], v[30:33], v[242:245], v[206:209]
	v_mfma_f32_16x16x32_bf16 v[210:213], v[38:41], v[242:245], v[210:213]
	ds_read_b128 v[230:233], v179
	ds_read_b128 v[234:237], v180
	ds_read_b32 v217, v137 offset:448
	v_max_f32_e32 v9, 0, v246
	v_max_f32_e32 v200, 0, v247
	v_max_f32_e32 v201, 0, v248
	v_max_f32_e32 v216, 0, v249
	v_mul_f32_e32 v62, v6, v9
	v_mul_f32_e32 v61, v6, v200
	v_mul_f32_e32 v64, v6, v201
	v_mul_f32_e32 v63, v6, v216
	v_max_f32_e32 v9, 0, v250
	v_max_f32_e32 v200, 0, v251
	v_max_f32_e32 v201, 0, v252
	v_max_f32_e32 v216, 0, v253
	v_mul_f32_e32 v66, v6, v9
	v_mul_f32_e32 v65, v6, v200
	v_mul_f32_e32 v68, v6, v201
	v_mul_f32_e32 v67, v6, v216
	s_waitcnt lgkmcnt(1)
	v_mfma_f32_16x16x32_bf16 v[246:249], v[26:29], v[230:233], 0
	v_mfma_f32_16x16x32_bf16 v[250:253], v[34:37], v[230:233], 0
	v_mfma_f32_16x16x32_bf16 v[246:249], v[30:33], v[234:237], v[246:249]
	v_mfma_f32_16x16x32_bf16 v[250:253], v[38:41], v[234:237], v[250:253]
	ds_read_b128 v[238:241], v176
	ds_read_b128 v[242:245], v159
	ds_read_b32 v6, v137 offset:512
	v_max_f32_e32 v9, 0, v206
	v_max_f32_e32 v200, 0, v207
	v_max_f32_e32 v201, 0, v208
	v_max_f32_e32 v216, 0, v209
	v_fmac_f32_e32 v62, v7, v9
	v_fmac_f32_e32 v61, v7, v200
	v_fmac_f32_e32 v64, v7, v201
	v_fmac_f32_e32 v63, v7, v216
	v_max_f32_e32 v9, 0, v210
	v_max_f32_e32 v200, 0, v211
	v_max_f32_e32 v201, 0, v212
	v_max_f32_e32 v216, 0, v213
	v_fmac_f32_e32 v66, v7, v9
	v_fmac_f32_e32 v65, v7, v200
	v_fmac_f32_e32 v68, v7, v201
	v_fmac_f32_e32 v67, v7, v216
	s_waitcnt lgkmcnt(1)
	v_mfma_f32_16x16x32_bf16 v[206:209], v[26:29], v[238:241], 0
	v_mfma_f32_16x16x32_bf16 v[210:213], v[34:37], v[238:241], 0
	v_mfma_f32_16x16x32_bf16 v[206:209], v[30:33], v[242:245], v[206:209]
	v_mfma_f32_16x16x32_bf16 v[210:213], v[38:41], v[242:245], v[210:213]
	ds_read_b128 v[230:233], v158
	ds_read_b128 v[234:237], v157
	ds_read_b32 v7, v137 offset:576
	v_max_f32_e32 v9, 0, v246
	v_max_f32_e32 v200, 0, v247
	v_max_f32_e32 v201, 0, v248
	v_max_f32_e32 v216, 0, v249
	v_fmac_f32_e32 v62, v217, v9
	v_fmac_f32_e32 v61, v217, v200
	v_fmac_f32_e32 v64, v217, v201
	v_fmac_f32_e32 v63, v217, v216
	v_max_f32_e32 v9, 0, v250
	v_max_f32_e32 v200, 0, v251
	v_max_f32_e32 v201, 0, v252
	v_max_f32_e32 v216, 0, v253
	v_fmac_f32_e32 v66, v217, v9
	v_fmac_f32_e32 v65, v217, v200
	v_fmac_f32_e32 v68, v217, v201
	v_fmac_f32_e32 v67, v217, v216
	s_waitcnt lgkmcnt(1)
	v_mfma_f32_16x16x32_bf16 v[246:249], v[26:29], v[230:233], 0
	v_mfma_f32_16x16x32_bf16 v[250:253], v[34:37], v[230:233], 0
	v_mfma_f32_16x16x32_bf16 v[246:249], v[30:33], v[234:237], v[246:249]
	v_mfma_f32_16x16x32_bf16 v[250:253], v[38:41], v[234:237], v[250:253]
	ds_read_b128 v[238:241], v156
	ds_read_b128 v[242:245], v155
	ds_read_b32 v217, v137 offset:640
	v_max_f32_e32 v9, 0, v206
	v_max_f32_e32 v200, 0, v207
	v_max_f32_e32 v201, 0, v208
	v_max_f32_e32 v216, 0, v209
	v_fmac_f32_e32 v62, v6, v9
	v_fmac_f32_e32 v61, v6, v200
	v_fmac_f32_e32 v64, v6, v201
	v_fmac_f32_e32 v63, v6, v216
	v_max_f32_e32 v9, 0, v210
	v_max_f32_e32 v200, 0, v211
	v_max_f32_e32 v201, 0, v212
	v_max_f32_e32 v216, 0, v213
	v_fmac_f32_e32 v66, v6, v9
	v_fmac_f32_e32 v65, v6, v200
	v_fmac_f32_e32 v68, v6, v201
	v_fmac_f32_e32 v67, v6, v216
	s_waitcnt lgkmcnt(1)
; #define LAS __attribute__((address_space(3)))
; __device__ __forceinline__ unsigned fkey(float f) { const unsigned u = __float_as_uint(f); return (u & 0x80000000u) ? ~u : (u | 0x80000000u); }
; #define SEL_HADD(idx_) __hip_atomic_fetch_add(&hist[(idx_)], 1u, __ATOMIC_RELAXED, __HIP_MEMORY_SCOPE_WORKGROUP)
; __device__ __forceinline__ void sel_unit(LAS char* lds, int b, int u, const bf16_t* QI, const bf16_t* KIDX, const float* WIDX, unsigned long long* MASK) {
;     ...
;             for (int kb = 0; kb < 2; ++kb) {
;                 f32x4 s = (f32x4){0.f, 0.f, 0.f, 0.f};
; #pragma unroll
;                 for (int hh = 0; hh < 8; ++hh) {
;                     f32x4 a = (f32x4){0.f, 0.f, 0.f, 0.f};
; #pragma unroll
;                     for (int ks = 0; ks < 2; ++ks) {
;                         const bf16x8 qv = *(const LAS bf16x8*)(lds + L_QI + q16 * 1024 + (((hh * 8 + 4 * ks + kg) ^ q16) << 4));
;                         a = __builtin_amdgcn_mfma_f32_16x16x32_bf16(kf[kb][ks], qv, a, 0, 0, 0);
;                     }
;                     const float wh = wl[hh * 16];
; #pragma unroll
;                     for (int i = 0; i < 4; ++i) s[i] += wh * fmaxf(a[i], 0.f);
;                 }
;                 u32x4 kk; kk.x = fkey(s[0]); kk.y = fkey(s[1]); kk.z = fkey(s[2]); kk.w = fkey(s[3]);
;                 sc[j][2 * kh + kb] = kk;
; #pragma unroll
;                 for (int i = 0; i < 4; ++i) SEL_HADD((kk[i] >> 24) * 16 + q16);
;                 __builtin_amdgcn_sched_barrier(0);
;             }
	v_mfma_f32_16x16x32_bf16 v[206:209], v[26:29], v[238:241], 0
	v_mfma_f32_16x16x32_bf16 v[210:213], v[34:37], v[238:241], 0
	v_mfma_f32_16x16x32_bf16 v[206:209], v[30:33], v[242:245], v[206:209]
	v_mfma_f32_16x16x32_bf16 v[210:213], v[38:41], v[242:245], v[210:213]
	ds_read_b128 v[230:233], v154
	ds_read_b128 v[234:237], v153
	ds_read_b32 v6, v137 offset:704
	v_max_f32_e32 v9, 0, v246
	v_max_f32_e32 v200, 0, v247
	v_max_f32_e32 v201, 0, v248
	v_max_f32_e32 v216, 0, v249
	v_fmac_f32_e32 v62, v7, v9
	v_fmac_f32_e32 v61, v7, v200
	v_fmac_f32_e32 v64, v7, v201
	v_fmac_f32_e32 v63, v7, v216
	v_max_f32_e32 v9, 0, v250
	v_max_f32_e32 v200, 0, v251
	v_max_f32_e32 v201, 0, v252
	v_max_f32_e32 v216, 0, v253
	v_fmac_f32_e32 v66, v7, v9
	v_fmac_f32_e32 v65, v7, v200
	v_fmac_f32_e32 v68, v7, v201
	v_fmac_f32_e32 v67, v7, v216
	s_waitcnt lgkmcnt(1)
	v_mfma_f32_16x16x32_bf16 v[246:249], v[26:29], v[230:233], 0
	v_mfma_f32_16x16x32_bf16 v[250:253], v[34:37], v[230:233], 0
	v_mfma_f32_16x16x32_bf16 v[246:249], v[30:33], v[234:237], v[246:249]
	v_mfma_f32_16x16x32_bf16 v[250:253], v[38:41], v[234:237], v[250:253]
	ds_read_b128 v[238:241], v152
	ds_read_b128 v[242:245], v151
	ds_read_b32 v7, v137 offset:768
	v_max_f32_e32 v9, 0, v206
	v_max_f32_e32 v200, 0, v207
	v_max_f32_e32 v201, 0, v208
	v_max_f32_e32 v216, 0, v209
	v_fmac_f32_e32 v62, v217, v9
	v_fmac_f32_e32 v61, v217, v200
	v_fmac_f32_e32 v64, v217, v201
	v_fmac_f32_e32 v63, v217, v216
	v_max_f32_e32 v9, 0, v210
	v_max_f32_e32 v200, 0, v211
	v_max_f32_e32 v201, 0, v212
	v_max_f32_e32 v216, 0, v213
	v_fmac_f32_e32 v66, v217, v9
	v_fmac_f32_e32 v65, v217, v200
	v_fmac_f32_e32 v68, v217, v201
	v_fmac_f32_e32 v67, v217, v216
	s_waitcnt lgkmcnt(1)
	v_mfma_f32_16x16x32_bf16 v[206:209], v[26:29], v[238:241], 0
	v_mfma_f32_16x16x32_bf16 v[210:213], v[34:37], v[238:241], 0
	v_mfma_f32_16x16x32_bf16 v[206:209], v[30:33], v[242:245], v[206:209]
	v_mfma_f32_16x16x32_bf16 v[210:213], v[38:41], v[242:245], v[210:213]
	v_max_f32_e32 v9, 0, v246
	v_max_f32_e32 v200, 0, v247
	v_max_f32_e32 v201, 0, v248
	v_max_f32_e32 v216, 0, v249
	v_fmac_f32_e32 v62, v6, v9
	v_fmac_f32_e32 v61, v6, v200
	v_fmac_f32_e32 v64, v6, v201
	v_fmac_f32_e32 v63, v6, v216
	v_max_f32_e32 v9, 0, v250
	v_max_f32_e32 v200, 0, v251
	v_max_f32_e32 v201, 0, v252
	v_max_f32_e32 v216, 0, v253
	v_fmac_f32_e32 v66, v6, v9
	v_fmac_f32_e32 v65, v6, v200
	v_fmac_f32_e32 v68, v6, v201
	v_fmac_f32_e32 v67, v6, v216
	s_waitcnt lgkmcnt(0)
	v_max_f32_e32 v9, 0, v206
	v_max_f32_e32 v200, 0, v207
	v_max_f32_e32 v201, 0, v208
	v_max_f32_e32 v216, 0, v209
	v_fmac_f32_e32 v62, v7, v9
	v_fmac_f32_e32 v61, v7, v200
	v_fmac_f32_e32 v64, v7, v201
	v_fmac_f32_e32 v63, v7, v216
	v_max_f32_e32 v9, 0, v210
	v_max_f32_e32 v200, 0, v211
	v_max_f32_e32 v201, 0, v212
	v_max_f32_e32 v216, 0, v213
	v_fmac_f32_e32 v66, v7, v9
	v_fmac_f32_e32 v65, v7, v200
	v_fmac_f32_e32 v68, v7, v201
	v_fmac_f32_e32 v67, v7, v216
	v_ashrrev_i32_e32 v9, 31, v62
	v_bitop3_b32 v62, v9, v62, v8 bitop3:0x36
	v_ashrrev_i32_e32 v200, 31, v61
	v_bitop3_b32 v61, v200, v61, v8 bitop3:0x36
	v_ashrrev_i32_e32 v201, 31, v64
	v_bitop3_b32 v64, v201, v64, v8 bitop3:0x36
	v_ashrrev_i32_e32 v216, 31, v63
	v_bitop3_b32 v63, v216, v63, v8 bitop3:0x36
	v_ashrrev_i32_e32 v9, 31, v66
	v_bitop3_b32 v66, v9, v66, v8 bitop3:0x36
	v_ashrrev_i32_e32 v200, 31, v65
	v_bitop3_b32 v65, v200, v65, v8 bitop3:0x36
	v_ashrrev_i32_e32 v201, 31, v68
	v_bitop3_b32 v68, v201, v68, v8 bitop3:0x36
	v_ashrrev_i32_e32 v216, 31, v67
	v_bitop3_b32 v67, v216, v67, v8 bitop3:0x36
	v_lshrrev_b32_e32 v9, 24, v62
	v_lshl_add_u32 v9, v9, 6, v0
	ds_add_u32 v9, v205 offset:16384
	v_lshrrev_b32_e32 v200, 24, v61
	v_lshl_add_u32 v200, v200, 6, v0
	ds_add_u32 v200, v205 offset:16384
	v_lshrrev_b32_e32 v201, 24, v64
	v_lshl_add_u32 v201, v201, 6, v0
	ds_add_u32 v201, v205 offset:16384
	v_lshrrev_b32_e32 v216, 24, v63
	v_lshl_add_u32 v216, v216, 6, v0
	ds_add_u32 v216, v205 offset:16384
	v_lshrrev_b32_e32 v9, 24, v66
	v_lshl_add_u32 v9, v9, 6, v0
	ds_add_u32 v9, v205 offset:16384
	v_lshrrev_b32_e32 v200, 24, v65
	v_lshl_add_u32 v200, v200, 6, v0
	ds_add_u32 v200, v205 offset:16384
	v_lshrrev_b32_e32 v201, 24, v68
	v_lshl_add_u32 v201, v201, 6, v0
	ds_add_u32 v201, v205 offset:16384
	v_lshrrev_b32_e32 v216, 24, v67
	v_lshl_add_u32 v216, v216, 6, v0
	ds_add_u32 v216, v205 offset:16384
	ds_read_b128 v[230:233], v182
	ds_read_b128 v[234:237], v183
	ds_read_b32 v6, v137 offset:320
	s_waitcnt vmcnt(0)
	s_cmp_lt_i32 s4, 2
	s_cbranch_scc1 .Lp0_nopf_0
	v_add_co_u32_e32 v22, vcc, 0xf000, v22
	s_nop 1
	v_addc_co_u32_e32 v23, vcc, 0, v23, vcc
	global_load_dwordx4 v[26:29], v[22:23], off
	global_load_dwordx4 v[30:33], v[22:23], off offset:64
	global_load_dwordx4 v[34:37], v[22:23], off offset:2048
	global_load_dwordx4 v[38:41], v[22:23], off offset:2112

; #define LAS __attribute__((address_space(3)))
; __device__ __forceinline__ void scan_hist(LAS char* lds, int shiftbits) {
;     LAS unsigned* hist = (LAS unsigned*)(lds + L_HIST); LAS unsigned* part = (LAS unsigned*)(lds + L_PART);
;     LAS unsigned* pref = (LAS unsigned*)(lds + L_PREF); LAS unsigned* kremS = (LAS unsigned*)(lds + L_KREM); LAS unsigned* neqS = (LAS unsigned*)(lds + L_NEQ);
;     const int tid = opaque_tid(), q = tid & 15, g = tid >> 4;
;     unsigned hv[8]; unsigned s = 0;
; #pragma unroll
;     for (int j = 0; j < 8; ++j) { hv[j] = hist[(8 * g + j) * 16 + q]; s += hv[j]; }
;     const unsigned krem = kremS[q];
;     part[g * 16 + q] = s;
;     __syncthreads();
;     unsigned above = 0;
; #pragma unroll
;     for (int gg = 0; gg < 32; ++gg) { const unsigned pv = part[gg * 16 + q]; above += (gg > g) ? pv : 0u; }
;     if (above < krem && krem <= above + s) {
;         unsigned cum = above; int bsel = 8 * g; unsigned hsel = 0; bool done = false;
; #pragma unroll
;         for (int j = 7; j >= 0; --j) { if (!done) { if (cum + hv[j] >= krem) { bsel = 8 * g + j; hsel = hv[j]; done = true; } else cum += hv[j]; } }
;         pref[q] = (pref[q] << shiftbits) | (unsigned)bsel; kremS[q] = krem - cum; neqS[q] = hsel;
;     }
;     __syncthreads();
.LBB0_672:
	s_waitcnt vmcnt(0) lgkmcnt(0)
	s_barrier
	s_getreg_b32 s2, hwreg(HW_REG_HW_ID, 0, 6)
	s_lshl_b32 s2, s2, 2
	s_and_b32 s2, s2, 0xfc
	s_add_i32 s2, s2, 0x20040
	v_mov_b32_e32 v2, s2
	ds_read_b32 v2, v2
	s_waitcnt lgkmcnt(0)
	v_readfirstlane_b32 s2, v2
	v_mov_b32_e32 v2, v1
	s_nop 0
	v_mbcnt_lo_u32_b32 v2, -1, v2
	v_mbcnt_hi_u32_b32 v2, -1, v2
	v_lshl_or_b32 v21, s2, 6, v2
	v_and_b32_e32 v2, 15, v2
	v_ashrrev_i32_e32 v20, 4, v21
	v_lshl_add_u32 v18, v2, 2, 0
	v_lshl_add_u32 v2, v20, 9, v18
	v_add_u32_e32 v4, 0x4000, v2
	ds_read2_b32 v[2:3], v4 offset1:16
	ds_read2_b32 v[6:7], v4 offset0:32 offset1:48
	ds_read2_b32 v[8:9], v4 offset0:64 offset1:80
	v_lshl_add_u32 v22, v21, 2, 0
	v_add_u32_e32 v25, 0x8000, v18
	s_waitcnt lgkmcnt(2)
	v_add_u32_e32 v5, v3, v2
	s_waitcnt lgkmcnt(1)
	v_add3_u32 v5, v5, v6, v7
	s_waitcnt lgkmcnt(0)
	v_add3_u32 v19, v5, v8, v9
	ds_read2_b32 v[4:5], v4 offset0:96 offset1:112
	v_ashrrev_i32_e32 v21, 31, v21
	v_cmp_gt_i32_e32 vcc, 1, v20
	s_waitcnt lgkmcnt(0)
	v_add3_u32 v24, v19, v4, v5
	ds_read_b32 v19, v18 offset:34944
	ds_write_b32 v22, v24 offset:32832
	s_waitcnt lgkmcnt(0)
	s_barrier
	ds_read2_b32 v[22:23], v25 offset0:16 offset1:32
	s_waitcnt lgkmcnt(0)
	v_and_b32_e32 v21, v21, v22
	v_cndmask_b32_e32 v22, 0, v23, vcc
	v_add_u32_e32 v21, v22, v21
	ds_read2_b32 v[22:23], v25 offset0:48 offset1:64
	v_cmp_gt_i32_e32 vcc, 2, v20
	s_waitcnt lgkmcnt(0)
	s_nop 0
	v_cndmask_b32_e32 v22, 0, v22, vcc
	v_cmp_gt_i32_e32 vcc, 3, v20
	s_nop 1
	v_cndmask_b32_e32 v23, 0, v23, vcc
	v_add3_u32 v21, v21, v22, v23
	ds_read2_b32 v[22:23], v25 offset0:80 offset1:96
	v_cmp_gt_i32_e32 vcc, 4, v20
	s_waitcnt lgkmcnt(0)
	s_nop 0
	v_cndmask_b32_e32 v22, 0, v22, vcc
	v_cmp_gt_i32_e32 vcc, 5, v20
	s_nop 1
	v_cndmask_b32_e32 v23, 0, v23, vcc
	v_add3_u32 v21, v21, v22, v23
	ds_read2_b32 v[22:23], v25 offset0:112 offset1:128
	v_cmp_gt_i32_e32 vcc, 6, v20
	s_waitcnt lgkmcnt(0)
	s_nop 0
	v_cndmask_b32_e32 v22, 0, v22, vcc
	v_cmp_gt_i32_e32 vcc, 7, v20
	s_nop 1
	v_cndmask_b32_e32 v23, 0, v23, vcc
	v_add3_u32 v21, v21, v22, v23
	ds_read2_b32 v[22:23], v25 offset0:144 offset1:160
	v_cmp_gt_i32_e32 vcc, 8, v20
	s_waitcnt lgkmcnt(0)
	s_nop 0
	v_cndmask_b32_e32 v22, 0, v22, vcc
	v_cmp_gt_i32_e32 vcc, 9, v20
	s_nop 1
	v_cndmask_b32_e32 v23, 0, v23, vcc
	v_add3_u32 v21, v21, v22, v23
	ds_read2_b32 v[22:23], v25 offset0:176 offset1:192
	v_cmp_gt_i32_e32 vcc, 10, v20
	s_waitcnt lgkmcnt(0)
	s_nop 0
	v_cndmask_b32_e32 v22, 0, v22, vcc
	v_cmp_gt_i32_e32 vcc, 11, v20
	s_nop 1
	v_cndmask_b32_e32 v23, 0, v23, vcc
	v_add3_u32 v21, v21, v22, v23
	ds_read2_b32 v[22:23], v25 offset0:208 offset1:224
	v_cmp_gt_i32_e32 vcc, 12, v20
	v_add_u32_e32 v25, 0x8400, v18
	s_waitcnt lgkmcnt(0)
	v_cndmask_b32_e32 v22, 0, v22, vcc
	v_cmp_gt_i32_e32 vcc, 13, v20
	s_nop 1
	v_cndmask_b32_e32 v23, 0, v23, vcc
	v_add3_u32 v21, v21, v22, v23
	v_add_u32_e32 v22, 0x8200, v18
	ds_read2_b32 v[22:23], v22 offset0:112 offset1:128
	v_cmp_gt_i32_e32 vcc, 14, v20
	s_waitcnt lgkmcnt(0)
	s_nop 0
	v_cndmask_b32_e32 v22, 0, v22, vcc
	v_cmp_gt_i32_e32 vcc, 15, v20
	s_nop 1
	v_cndmask_b32_e32 v23, 0, v23, vcc
	v_add3_u32 v21, v21, v22, v23
	ds_read2_b32 v[22:23], v25 offset0:16 offset1:32
	v_cmp_gt_i32_e32 vcc, 16, v20
	s_waitcnt lgkmcnt(0)
	s_nop 0
	v_cndmask_b32_e32 v22, 0, v22, vcc
	v_cmp_gt_i32_e32 vcc, 17, v20
	s_nop 1
	v_cndmask_b32_e32 v23, 0, v23, vcc
	v_add3_u32 v21, v21, v22, v23
	ds_read2_b32 v[22:23], v25 offset0:48 offset1:64
	v_cmp_gt_i32_e32 vcc, 18, v20
	s_waitcnt lgkmcnt(0)
	s_nop 0
	v_cndmask_b32_e32 v22, 0, v22, vcc
	v_cmp_gt_i32_e32 vcc, 19, v20
	s_nop 1
	v_cndmask_b32_e32 v23, 0, v23, vcc
	v_add3_u32 v21, v21, v22, v23
	ds_read2_b32 v[22:23], v25 offset0:80 offset1:96
	v_cmp_gt_i32_e32 vcc, 20, v20
	s_waitcnt lgkmcnt(0)
	s_nop 0
	v_cndmask_b32_e32 v22, 0, v22, vcc
	v_cmp_gt_i32_e32 vcc, 21, v20
	s_nop 1
	v_cndmask_b32_e32 v23, 0, v23, vcc
	v_add3_u32 v21, v21, v22, v23
	ds_read2_b32 v[22:23], v25 offset0:112 offset1:128
	v_cmp_gt_i32_e32 vcc, 22, v20
	s_waitcnt lgkmcnt(0)
	s_nop 0
	v_cndmask_b32_e32 v22, 0, v22, vcc
	v_cmp_gt_i32_e32 vcc, 23, v20
	s_nop 1
	v_cndmask_b32_e32 v23, 0, v23, vcc
	v_add3_u32 v21, v21, v22, v23
	ds_read2_b32 v[22:23], v25 offset0:144 offset1:160
	v_cmp_gt_i32_e32 vcc, 24, v20
	s_waitcnt lgkmcnt(0)
	s_nop 0
	v_cndmask_b32_e32 v22, 0, v22, vcc
	v_cmp_gt_i32_e32 vcc, 25, v20
	s_nop 1
	v_cndmask_b32_e32 v23, 0, v23, vcc
	v_add3_u32 v21, v21, v22, v23
	ds_read2_b32 v[22:23], v25 offset0:176 offset1:192
	v_cmp_gt_i32_e32 vcc, 26, v20
	s_waitcnt lgkmcnt(0)
	s_nop 0
	v_cndmask_b32_e32 v22, 0, v22, vcc
	v_cmp_gt_i32_e32 vcc, 27, v20
	s_nop 1
	v_cndmask_b32_e32 v23, 0, v23, vcc
	v_add3_u32 v21, v21, v22, v23
	ds_read2_b32 v[22:23], v25 offset0:208 offset1:224
	v_cmp_gt_i32_e32 vcc, 28, v20
	s_waitcnt lgkmcnt(0)
	s_nop 0
	v_cndmask_b32_e32 v22, 0, v22, vcc
	v_cmp_gt_i32_e32 vcc, 29, v20
	s_nop 1
	v_cndmask_b32_e32 v23, 0, v23, vcc
	v_add3_u32 v21, v21, v22, v23
	v_add_u32_e32 v22, 0x8600, v18
	ds_read2_b32 v[22:23], v22 offset0:112 offset1:128
	v_cmp_gt_i32_e32 vcc, 30, v20
	s_waitcnt lgkmcnt(0)
	s_nop 0
	v_cndmask_b32_e32 v22, 0, v22, vcc
	v_cmp_gt_i32_e32 vcc, 31, v20
	s_nop 1
	v_cndmask_b32_e32 v23, 0, v23, vcc
	v_add3_u32 v22, v21, v22, v23
	v_add_u32_e32 v21, v22, v24
	v_cmp_lt_u32_e32 vcc, v22, v19
	v_cmp_le_u32_e64 s[2:3], v19, v21
	s_and_b64 s[2:3], vcc, s[2:3]
	s_and_saveexec_b64 s[4:5], s[2:3]
	s_xor_b64 s[2:3], exec, s[4:5]
	s_cbranch_execz .LBB0_702
	v_lshlrev_b32_e32 v20, 3, v20
	v_add_u32_e32 v23, v22, v5
	v_cmp_lt_u32_e32 vcc, v23, v19
	v_or_b32_e32 v21, 7, v20
	s_mov_b64 s[4:5], -1
	s_mov_b64 s[8:9], -1
	s_and_saveexec_b64 s[6:7], vcc
	s_cbranch_execz .LBB0_677
	v_add_u32_e32 v22, v23, v4
	v_cmp_ge_u32_e32 vcc, v22, v19
	v_mov_b32_e32 v5, 0
	s_mov_b64 s[8:9], 0
	v_mov_b32_e32 v21, v20
	s_and_saveexec_b64 s[10:11], vcc
	s_mov_b64 s[8:9], exec
	v_or_b32_e32 v21, 6, v20
	v_mov_b32_e32 v5, v4
	v_mov_b32_e32 v22, v23
	s_or_b64 exec, exec, s[10:11]
	s_orn2_b64 s[8:9], s[8:9], exec
